# attention tile loops (NSA selected/window, MLA): next tile's K/V staged into LDS before the PV MFMAs of the current tile instead of at the top of the next iteration; on top of v51
# baseline (speedup 1.0000x reference)
; #define LAS __attribute__((address_space(3)))
; template <bool HASP, bool HASV>
; __device__ __forceinline__ void stage_store(const Stage& st, LAS unsigned char* kbuf, LAS unsigned char* vbuf, int tid) {
;     const int r0 = tid >> 4, c0 = (tid & 15) * 16;
;     *(LAS u32x4*)(kbuf + r0 * KP + c0) = st.k0; *(LAS u32x4*)(kbuf + (r0 + 32) * KP + c0) = st.k1;
;     if (HASP) *(LAS u32x4*)(kbuf + (tid >> 3) * KP + 256 + (tid & 7) * 16) = st.kp;
;     if (HASV) { *(LAS u32x4*)(vbuf + r0 * VP + c0) = st.v0; *(LAS u32x4*)(vbuf + (r0 + 32) * VP + c0) = st.v1; }
; }
; template <int MODE, int NQ> ...
;     ...
;     int j; unsigned long long rem = 0ull;
;     if (MODE == M_SEL) { rem = tmask; j = rem ? (int)__builtin_ctzll(rem) : -1; rem &= rem - 1ull; } else { j = jlo <= jhi ? jlo : -1; }
;     Stage st;
;     __syncthreads();
;     if (j >= 0) stage_load<HASP, HASV>(st, Kg + (size_t)j * 64 * ldk, ldk, Pg + (size_t)j * 64 * 64, Vg + (size_t)j * 64 * ldv, ldv, tid);
;     int it = 0;
;     while (j >= 0) {
;         const int bsel = it & 1;
;         stage_store<HASP, HASV>(st, lds + OFF_K + bsel * KBUF, lds + OFF_V + bsel * VBUF, tid);
;         __syncthreads();
;         int jn;
;         if (MODE == M_SEL) { jn = rem ? (int)__builtin_ctzll(rem) : -1; rem &= rem - 1ull; } else { jn = (j + 1 <= jhi) ? j + 1 : -1; }
;         if (jn >= 0) stage_load<HASP, HASV>(st, Kg + (size_t)jn * 64 * ldk, ldk, Pg + (size_t)jn * 64 * 64, Vg + (size_t)jn * 64 * ldv, ldv, tid);
.Lsel_pf_ok:
	v_mov_b32_e32 v16, v151
	v_mov_b32_e32 v17, v151
	v_mov_b32_e32 v2, v151
	v_mov_b32_e32 v3, v151
	v_mov_b32_e32 v4, v151
	v_mov_b32_e32 v5, v151
	v_mov_b32_e32 v6, v151
	v_mov_b32_e32 v7, v151
	v_mov_b32_e32 v8, v151
	v_mov_b32_e32 v9, v151
	v_mov_b32_e32 v10, v151
	v_mov_b32_e32 v11, v151
	v_mov_b32_e32 v12, v151
	v_mov_b32_e32 v13, v151
	v_mov_b32_e32 v14, v151
	v_mov_b32_e32 v15, v151
	v_mov_b32_e32 v146, 0
	v_mov_b64_e32 v[32:33], v[16:17]
	v_mov_b64_e32 v[48:49], v[16:17]
	v_mov_b64_e32 v[64:65], v[16:17]
	s_mov_b32 s5, 0
	v_mov_b32_e32 v211, 0xf149f2ca
	v_mov_b64_e32 v[30:31], v[14:15]
	v_mov_b64_e32 v[28:29], v[12:13]
	v_mov_b64_e32 v[26:27], v[10:11]
	v_mov_b64_e32 v[24:25], v[8:9]
	v_mov_b64_e32 v[22:23], v[6:7]
	v_mov_b64_e32 v[20:21], v[4:5]
	v_mov_b64_e32 v[18:19], v[2:3]
	v_mov_b64_e32 v[46:47], v[14:15]
	v_mov_b64_e32 v[44:45], v[12:13]
	v_mov_b64_e32 v[42:43], v[10:11]
	v_mov_b64_e32 v[40:41], v[8:9]
	v_mov_b64_e32 v[38:39], v[6:7]
	v_mov_b64_e32 v[36:37], v[4:5]
	v_mov_b64_e32 v[34:35], v[2:3]
	v_mov_b64_e32 v[62:63], v[14:15]
	v_mov_b64_e32 v[60:61], v[12:13]
	v_mov_b64_e32 v[58:59], v[10:11]
	v_mov_b64_e32 v[56:57], v[8:9]
	v_mov_b64_e32 v[54:55], v[6:7]
	v_mov_b64_e32 v[52:53], v[4:5]
	v_mov_b64_e32 v[50:51], v[2:3]
	v_mov_b32_e32 v78, 0
	v_mov_b32_e32 v79, v146
	v_mov_b32_e32 v80, 0
	v_mov_b32_e32 v81, v146
	v_mov_b32_e32 v74, 0
	v_mov_b32_e32 v75, v146
	v_mov_b32_e32 v76, 0
	v_mov_b32_e32 v77, v146
	v_mov_b32_e32 v70, 0
	v_mov_b32_e32 v71, v146
	v_mov_b32_e32 v72, 0
	v_mov_b32_e32 v73, v146
	v_mov_b32_e32 v66, 0
	v_mov_b32_e32 v67, v146
	v_mov_b32_e32 v68, 0
	v_mov_b32_e32 v69, v146
	v_mov_b32_e32 v94, 0
	v_mov_b32_e32 v95, v146
	v_mov_b32_e32 v96, 0
	v_mov_b32_e32 v97, v146
	v_mov_b32_e32 v90, 0
	v_mov_b32_e32 v91, v146
	v_mov_b32_e32 v92, 0
	v_mov_b32_e32 v93, v146
	v_mov_b32_e32 v86, 0
	v_mov_b32_e32 v87, v146
	v_mov_b32_e32 v88, 0
	v_mov_b32_e32 v89, v146
	v_mov_b32_e32 v82, 0
	v_mov_b32_e32 v83, v146
	v_mov_b32_e32 v84, 0
	v_mov_b32_e32 v85, v146
	v_mov_b32_e32 v190, 0
	v_mov_b32_e32 v191, v146
	v_mov_b32_e32 v192, 0
	v_mov_b32_e32 v193, v146
	v_mov_b32_e32 v180, 0
	v_mov_b32_e32 v181, v146
	v_mov_b32_e32 v182, 0
	v_mov_b32_e32 v183, v146
	v_mov_b32_e32 v176, 0
	v_mov_b32_e32 v177, v146
	v_mov_b32_e32 v178, 0
	v_mov_b32_e32 v179, v146
	v_mov_b32_e32 v172, 0
	v_mov_b32_e32 v173, v146
	v_mov_b32_e32 v174, 0
	v_mov_b32_e32 v175, v146
	v_mov_b32_e32 v202, 0
	v_mov_b32_e32 v203, v146
	v_mov_b32_e32 v204, 0
	v_mov_b32_e32 v205, v146
	v_mov_b32_e32 v198, 0
	v_mov_b32_e32 v199, v146
	v_mov_b32_e32 v200, 0
	v_mov_b32_e32 v201, v146
	v_mov_b32_e32 v194, 0
	v_mov_b32_e32 v195, v146
	v_mov_b32_e32 v196, 0
	v_mov_b32_e32 v197, v146
	v_mov_b32_e32 v184, 0
	v_mov_b32_e32 v185, v146
	v_mov_b32_e32 v188, 0
	v_mov_b32_e32 v189, v146
	s_mov_b32 s99, 0
.LBB0_921:
	s_and_b32 s10, s5, 1
	s_mul_i32 s9, s10, 0x6400
	s_add_i32 s2, s9, 0
	s_mul_i32 s3, s10, 0xffffec00
	s_add_i32 s3, s2, s3
	s_xor_b32 s100, s10, 1
	s_mul_i32 s101, s100, 0x5000
	s_mul_i32 s100, s100, 0x6400
	s_cmp_eq_u32 s99, 0
	s_mov_b32 s99, 0
	s_cbranch_scc0 .Lst_sel_top
	v_add3_u32 v163, s2, v187, v165
	s_waitcnt vmcnt(3)
	ds_write_b128 v163, v[130:133]
	v_add3_u32 v163, s2, v207, v165
	s_waitcnt vmcnt(1)
	ds_write_b128 v163, v[138:141]
	v_add3_u32 v163, s3, v208, v165
	ds_write_b128 v163, v[134:137] offset:51200
	v_add3_u32 v163, s3, v209, v165
	s_waitcnt vmcnt(0)
	ds_write_b128 v163, v[142:145] offset:51200
.Lst_sel_top:
	s_cmp_eq_u64 s[0:1], 0
	s_cselect_b64 s[6:7], -1, 0
	s_cselect_b32 s98, 0, 1
	s_ff1_i32_b64 s4, s[0:1]
	s_and_b64 vcc, exec, s[6:7]
	s_waitcnt lgkmcnt(0)
	s_barrier
	s_cbranch_vccnz .LBB0_923
	s_mul_i32 s2, s4, 0x60000
	s_add_u32 s2, s65, s2
	s_addc_u32 s3, s69, 0
	v_lshl_add_u64 v[130:131], v[166:167], 1, s[2:3]
	v_lshl_add_u64 v[134:135], v[130:131], 0, v[150:151]
	v_lshl_add_u64 v[130:131], v[168:169], 1, s[2:3]
	v_lshl_add_u64 v[142:143], v[130:131], 0, v[150:151]
	global_load_dwordx4 v[130:133], v[134:135], off offset:2048
	s_nop 0
	global_load_dwordx4 v[134:137], v[134:135], off offset:3072
	s_nop 0
	global_load_dwordx4 v[138:141], v[142:143], off offset:2048
	s_nop 0
	global_load_dwordx4 v[142:145], v[142:143], off offset:3072

; #define LAS __attribute__((address_space(3)))
; template <bool HASP, bool HASV>
; __device__ __forceinline__ void stage_store(const Stage& st, LAS unsigned char* kbuf, LAS unsigned char* vbuf, int tid) {
;     const int r0 = tid >> 4, c0 = (tid & 15) * 16;
;     *(LAS u32x4*)(kbuf + r0 * KP + c0) = st.k0; *(LAS u32x4*)(kbuf + (r0 + 32) * KP + c0) = st.k1;
;     if (HASP) *(LAS u32x4*)(kbuf + (tid >> 3) * KP + 256 + (tid & 7) * 16) = st.kp;
;     if (HASV) { *(LAS u32x4*)(vbuf + r0 * VP + c0) = st.v0; *(LAS u32x4*)(vbuf + (r0 + 32) * VP + c0) = st.v1; }
; }
.LBB0_928:
	s_cmp_eq_u32 s98, 0
	s_cbranch_scc1 .Lst_sel_mid
	v_add3_u32 v254, s100, v187, v165
	s_waitcnt vmcnt(3)
	ds_write_b128 v254, v[130:133]
	v_add3_u32 v254, s100, v207, v165
	s_waitcnt vmcnt(1)
	ds_write_b128 v254, v[138:141]
	v_add3_u32 v254, s101, v208, v165
	ds_write_b128 v254, v[134:137] offset:51200
	v_add3_u32 v254, s101, v209, v165
	s_waitcnt vmcnt(0)
	ds_write_b128 v254, v[142:145] offset:51200
	s_mov_b32 s99, 1

; __device__ __forceinline__ u32x2 pack4(f32x4 v) { u32x2 w; w.x = cvtpk(v[0], v[1]); w.y = cvtpk(v[2], v[3]); return w; }
; __device__ __forceinline__ void nsa_unit(Frame& F, int b, int g, int c) {
;     ...
;     { const float sc = l > 0.f ? gs / l : 0.f;
; #pragma unroll
;       for (int db = 0; db < 4; ++db)
; #pragma unroll
;           for (int q4 = 0; q4 < 4; ++q4) { bf16_t* p = accb + 32 * db + 8 * q4 + 4 * hi; f32x4 o = {O[db][4 * q4], O[db][4 * q4 + 1], O[db][4 * q4 + 2], O[db][4 * q4 + 3]}; const u32x2 w = *(const u32x2*)p;
;               const f32x4 pr = {__uint_as_float(w.x << 16), __uint_as_float(w.x & 0xffff0000u), __uint_as_float(w.y << 16), __uint_as_float(w.y & 0xffff0000u)}; *(u32x2*)p = pack4(pr + o * sc); } }
;     m = -1e30f; l = 0.f; zero_o(O);
;     run_seq<M_WIN, 8>(lds, tid, qf, O, m, l, C, KV + 4 * 512, 3072, KV, KV + 5 * 512, 3072, c >= 8 ? c - 8 : 0, c, 0ull, ts, ts - 512, 0ull, 0, 0.f, tokl, head);
.LBB0_936:
	v_sub_u32_e64 v144, s68, 8 clamp
	s_mov_b32 s99, 0x60000
	v_mul_lo_u32 v144, v144, s99
	v_mov_b32_e32 v145, v151
	v_lshl_add_u64 v[142:143], s[90:91], 0, v[144:145]
	v_lshl_add_u64 v[140:141], v[166:167], 1, v[142:143]
	v_lshl_add_u64 v[140:141], v[140:141], 0, v[150:151]
	global_load_dwordx4 v[130:133], v[140:141], off
	v_lshl_add_u64 v[140:141], v[168:169], 1, v[142:143]
	v_lshl_add_u64 v[140:141], v[140:141], 0, v[150:151]
	global_load_dwordx4 v[134:137], v[140:141], off
	v_lshl_add_u64 v[142:143], s[92:93], 0, v[144:145]
	v_lshl_add_u64 v[140:141], v[166:167], 1, v[142:143]
	v_lshl_add_u64 v[140:141], v[140:141], 0, v[150:151]
	global_load_dwordx4 v[138:141], v[140:141], off
	v_lshl_add_u64 v[144:145], v[168:169], 1, v[142:143]
	v_lshl_add_u64 v[144:145], v[144:145], 0, v[150:151]
	global_load_dwordx4 v[142:145], v[144:145], off
	v_div_scale_f32 v32, s[0:1], v146, v146, v147
	v_rcp_f32_e32 v34, v32
	v_div_scale_f32 v33, vcc, v147, v146, v147
	v_fma_f32 v35, -v32, v34, 1.0
	v_fmac_f32_e32 v34, v35, v34
	v_mul_f32_e32 v35, v33, v34
	v_fma_f32 v36, -v32, v35, v33
	v_fmac_f32_e32 v35, v36, v34
	v_fma_f32 v32, -v32, v35, v33
	v_div_fmas_f32 v32, v32, v34, v35
	v_div_fixup_f32 v32, v32, v146, v147
	v_cmp_lt_f32_e32 vcc, 0, v146
	s_mov_b32 s0, 0x60000
	v_lshlrev_b64 v[146:147], 1, v[166:167]
	v_cndmask_b32_e32 v32, 0, v32, vcc
	v_lshlrev_b64 v[162:163], 1, v[168:169]
	s_mov_b32 s2, 0
	v_mov_b32_e32 v166, 0
	v_mov_b32_e32 v168, 0xf149f2ca
	v_lshlrev_b32_e32 v34, 16, v220
	v_and_b32_e32 v35, 0xffff0000, v220
	v_lshlrev_b32_e32 v2, 16, v221
	v_and_b32_e32 v3, 0xffff0000, v221
	v_lshlrev_b32_e32 v36, 16, v222
	v_and_b32_e32 v37, 0xffff0000, v222
	v_lshlrev_b32_e32 v4, 16, v223
	v_and_b32_e32 v5, 0xffff0000, v223
	v_lshlrev_b32_e32 v38, 16, v224
	v_and_b32_e32 v39, 0xffff0000, v224
	v_lshlrev_b32_e32 v6, 16, v225
	v_and_b32_e32 v7, 0xffff0000, v225
	v_lshlrev_b32_e32 v40, 16, v226
	v_and_b32_e32 v41, 0xffff0000, v226
	v_lshlrev_b32_e32 v8, 16, v227
	v_and_b32_e32 v9, 0xffff0000, v227
	v_lshlrev_b32_e32 v42, 16, v228
	v_and_b32_e32 v43, 0xffff0000, v228
	v_lshlrev_b32_e32 v10, 16, v229
	v_and_b32_e32 v11, 0xffff0000, v229
	v_lshlrev_b32_e32 v44, 16, v230
	v_and_b32_e32 v45, 0xffff0000, v230
	v_lshlrev_b32_e32 v12, 16, v231
	v_and_b32_e32 v13, 0xffff0000, v231
	v_pk_fma_f32 v[2:3], v[204:205], v[32:33], v[2:3] op_sel_hi:[1,0,1]
	v_pk_fma_f32 v[34:35], v[202:203], v[32:33], v[34:35] op_sel_hi:[1,0,1]
	v_pk_fma_f32 v[4:5], v[200:201], v[32:33], v[4:5] op_sel_hi:[1,0,1]
	v_pk_fma_f32 v[36:37], v[198:199], v[32:33], v[36:37] op_sel_hi:[1,0,1]
	v_pk_fma_f32 v[6:7], v[196:197], v[32:33], v[6:7] op_sel_hi:[1,0,1]
	v_pk_fma_f32 v[38:39], v[194:195], v[32:33], v[38:39] op_sel_hi:[1,0,1]
	v_pk_fma_f32 v[8:9], v[188:189], v[32:33], v[8:9] op_sel_hi:[1,0,1]
	v_pk_fma_f32 v[40:41], v[184:185], v[32:33], v[40:41] op_sel_hi:[1,0,1]
	v_pk_fma_f32 v[10:11], v[192:193], v[32:33], v[10:11] op_sel_hi:[1,0,1]
	v_pk_fma_f32 v[42:43], v[190:191], v[32:33], v[42:43] op_sel_hi:[1,0,1]
	v_pk_fma_f32 v[12:13], v[182:183], v[32:33], v[12:13] op_sel_hi:[1,0,1]
	v_pk_fma_f32 v[44:45], v[180:181], v[32:33], v[44:45] op_sel_hi:[1,0,1]
	v_cvt_pk_bf16_f32 v220, v34, v35
	v_cvt_pk_bf16_f32 v221, v2, v3
	v_cvt_pk_bf16_f32 v222, v36, v37
	v_cvt_pk_bf16_f32 v223, v4, v5
	v_cvt_pk_bf16_f32 v224, v38, v39
	v_cvt_pk_bf16_f32 v225, v6, v7
	v_cvt_pk_bf16_f32 v226, v40, v41
	v_cvt_pk_bf16_f32 v227, v8, v9
	v_cvt_pk_bf16_f32 v228, v42, v43
	v_cvt_pk_bf16_f32 v229, v10, v11
	v_cvt_pk_bf16_f32 v230, v44, v45
	v_cvt_pk_bf16_f32 v231, v12, v13
	v_lshlrev_b32_e32 v2, 16, v232
	v_and_b32_e32 v3, 0xffff0000, v232
	v_lshlrev_b32_e32 v6, 16, v233
	v_and_b32_e32 v7, 0xffff0000, v233
	v_pk_fma_f32 v[6:7], v[178:179], v[32:33], v[6:7] op_sel_hi:[1,0,1]
	v_pk_fma_f32 v[2:3], v[176:177], v[32:33], v[2:3] op_sel_hi:[1,0,1]
	v_sub_u32_e64 v8, s68, 8 clamp
	v_cvt_pk_bf16_f32 v232, v2, v3
	v_cvt_pk_bf16_f32 v233, v6, v7
	v_lshlrev_b32_e32 v2, 16, v234
	v_and_b32_e32 v3, 0xffff0000, v234
	v_lshlrev_b32_e32 v6, 16, v235
	v_and_b32_e32 v7, 0xffff0000, v235
	v_pk_fma_f32 v[6:7], v[174:175], v[32:33], v[6:7] op_sel_hi:[1,0,1]
	v_pk_fma_f32 v[2:3], v[172:173], v[32:33], v[2:3] op_sel_hi:[1,0,1]
	v_mov_b32_e32 v16, v151
	v_cvt_pk_bf16_f32 v234, v2, v3
	v_cvt_pk_bf16_f32 v235, v6, v7
	v_lshlrev_b32_e32 v2, 16, v236
	v_and_b32_e32 v3, 0xffff0000, v236
	v_lshlrev_b32_e32 v6, 16, v237
	v_and_b32_e32 v7, 0xffff0000, v237
	v_pk_fma_f32 v[6:7], v[96:97], v[32:33], v[6:7] op_sel_hi:[1,0,1]
	v_pk_fma_f32 v[2:3], v[94:95], v[32:33], v[2:3] op_sel_hi:[1,0,1]
	v_mov_b32_e32 v17, v151
	v_cvt_pk_bf16_f32 v236, v2, v3
	v_cvt_pk_bf16_f32 v237, v6, v7
	v_lshlrev_b32_e32 v2, 16, v238
	v_and_b32_e32 v3, 0xffff0000, v238
	v_lshlrev_b32_e32 v6, 16, v239
	v_and_b32_e32 v7, 0xffff0000, v239
	v_pk_fma_f32 v[6:7], v[92:93], v[32:33], v[6:7] op_sel_hi:[1,0,1]
	v_pk_fma_f32 v[2:3], v[90:91], v[32:33], v[2:3] op_sel_hi:[1,0,1]
	v_readfirstlane_b32 s3, v8
	v_cvt_pk_bf16_f32 v238, v2, v3
	v_cvt_pk_bf16_f32 v239, v6, v7
	v_lshlrev_b32_e32 v2, 16, v240
	v_and_b32_e32 v3, 0xffff0000, v240
	v_lshlrev_b32_e32 v6, 16, v241
	v_and_b32_e32 v7, 0xffff0000, v241
; __device__ __forceinline__ u32x2 pack4(f32x4 v) { u32x2 w; w.x = cvtpk(v[0], v[1]); w.y = cvtpk(v[2], v[3]); return w; }
; template <int MODE, int NQ> ...
;     ...
;     while (j >= 0) {
;         const int bsel = it & 1;
;         stage_store<HASP, HASV>(st, lds + OFF_K + bsel * KBUF, lds + OFF_V + bsel * VBUF, tid);
;         __syncthreads();
;         int jn;
;         if (MODE == M_SEL) { jn = rem ? (int)__builtin_ctzll(rem) : -1; rem &= rem - 1ull; } else { jn = (j + 1 <= jhi) ? j + 1 : -1; }
;         if (jn >= 0) stage_load<HASP, HASV>(st, Kg + (size_t)jn * 64 * ldk, ldk, Pg + (size_t)jn * 64 * 64, Vg + (size_t)jn * 64 * ldv, ldv, tid);
; __device__ __forceinline__ void nsa_unit(Frame& F, int b, int g, int c) {
;     ...
;     { const float sc = l > 0.f ? gs / l : 0.f;
; #pragma unroll
;       for (int db = 0; db < 4; ++db)
; #pragma unroll
;           for (int q4 = 0; q4 < 4; ++q4) { bf16_t* p = accb + 32 * db + 8 * q4 + 4 * hi; f32x4 o = {O[db][4 * q4], O[db][4 * q4 + 1], O[db][4 * q4 + 2], O[db][4 * q4 + 3]}; const u32x2 w = *(const u32x2*)p;
;               const f32x4 pr = {__uint_as_float(w.x << 16), __uint_as_float(w.x & 0xffff0000u), __uint_as_float(w.y << 16), __uint_as_float(w.y & 0xffff0000u)}; *(u32x2*)p = pack4(pr + o * sc); } }
;     m = -1e30f; l = 0.f; zero_o(O);
;     run_seq<M_WIN, 8>(lds, tid, qf, O, m, l, C, KV + 4 * 512, 3072, KV, KV + 5 * 512, 3072, c >= 8 ? c - 8 : 0, c, 0ull, ts, ts - 512, 0ull, 0, 0.f, tokl, head);
	v_pk_fma_f32 v[6:7], v[88:89], v[32:33], v[6:7] op_sel_hi:[1,0,1]
	v_pk_fma_f32 v[2:3], v[86:87], v[32:33], v[2:3] op_sel_hi:[1,0,1]
	v_mov_b32_e32 v9, v151
	v_cvt_pk_bf16_f32 v240, v2, v3
	v_cvt_pk_bf16_f32 v241, v6, v7
	v_lshlrev_b32_e32 v2, 16, v242
	v_and_b32_e32 v3, 0xffff0000, v242
	v_lshlrev_b32_e32 v6, 16, v243
	v_and_b32_e32 v7, 0xffff0000, v243
	v_pk_fma_f32 v[6:7], v[84:85], v[32:33], v[6:7] op_sel_hi:[1,0,1]
	v_pk_fma_f32 v[2:3], v[82:83], v[32:33], v[2:3] op_sel_hi:[1,0,1]
	v_mov_b32_e32 v10, v151
	v_cvt_pk_bf16_f32 v242, v2, v3
	v_cvt_pk_bf16_f32 v243, v6, v7
	v_lshlrev_b32_e32 v2, 16, v246
	v_and_b32_e32 v3, 0xffff0000, v246
	v_lshlrev_b32_e32 v6, 16, v247
	v_and_b32_e32 v7, 0xffff0000, v247
	v_pk_fma_f32 v[6:7], v[80:81], v[32:33], v[6:7] op_sel_hi:[1,0,1]
	v_pk_fma_f32 v[2:3], v[78:79], v[32:33], v[2:3] op_sel_hi:[1,0,1]
	v_mov_b32_e32 v11, v151
	v_cvt_pk_bf16_f32 v246, v2, v3
	v_cvt_pk_bf16_f32 v247, v6, v7
	v_lshlrev_b32_e32 v2, 16, v248
	v_and_b32_e32 v3, 0xffff0000, v248
	v_lshlrev_b32_e32 v6, 16, v249
	v_and_b32_e32 v7, 0xffff0000, v249
	v_pk_fma_f32 v[6:7], v[76:77], v[32:33], v[6:7] op_sel_hi:[1,0,1]
	v_pk_fma_f32 v[2:3], v[74:75], v[32:33], v[2:3] op_sel_hi:[1,0,1]
	v_mov_b32_e32 v12, v151
	v_cvt_pk_bf16_f32 v248, v2, v3
	v_cvt_pk_bf16_f32 v249, v6, v7
	v_lshlrev_b32_e32 v2, 16, v250
	v_and_b32_e32 v3, 0xffff0000, v250
	v_lshlrev_b32_e32 v6, 16, v251
	v_and_b32_e32 v7, 0xffff0000, v251
	v_pk_fma_f32 v[6:7], v[72:73], v[32:33], v[6:7] op_sel_hi:[1,0,1]
	v_pk_fma_f32 v[2:3], v[70:71], v[32:33], v[2:3] op_sel_hi:[1,0,1]
	v_mov_b32_e32 v13, v151
	v_cvt_pk_bf16_f32 v250, v2, v3
	v_cvt_pk_bf16_f32 v251, v6, v7
	v_lshlrev_b32_e32 v2, 16, v252
	v_and_b32_e32 v3, 0xffff0000, v252
	v_lshlrev_b32_e32 v4, 16, v253
	v_and_b32_e32 v5, 0xffff0000, v253
	v_pk_fma_f32 v[4:5], v[68:69], v[32:33], v[4:5] op_sel_hi:[1,0,1]
	v_pk_fma_f32 v[2:3], v[66:67], v[32:33], v[2:3] op_sel_hi:[1,0,1]
	v_mov_b32_e32 v14, v151
	v_cvt_pk_bf16_f32 v252, v2, v3
	v_cvt_pk_bf16_f32 v253, v4, v5
	v_mul_lo_u32 v2, v8, s0
	v_mov_b32_e32 v3, v151
	v_lshl_add_u64 v[4:5], s[90:91], 0, v[2:3]
	v_lshl_add_u64 v[6:7], v[4:5], 0, v[146:147]
	v_lshl_add_u64 v[4:5], v[4:5], 0, v[162:163]
	v_lshl_add_u64 v[2:3], s[92:93], 0, v[2:3]
	v_lshl_add_u64 v[6:7], v[6:7], 0, v[150:151]
	v_lshl_add_u64 v[4:5], v[4:5], 0, v[150:151]
	s_barrier
	v_lshl_add_u64 v[4:5], v[2:3], 0, v[146:147]
	v_lshl_add_u64 v[4:5], v[4:5], 0, v[150:151]
	v_lshl_add_u64 v[2:3], v[2:3], 0, v[162:163]
	v_lshl_add_u64 v[2:3], v[2:3], 0, v[150:151]
	s_min_u32 s0, s68, 8
	s_lshl_b32 s0, s0, 6
	s_add_i32 s0, s0, s74
	v_add_u32_e32 v2, s0, v210
	v_sub_u32_e32 v164, v2, v158
	v_mov_b32_e32 v2, v151
	v_mov_b32_e32 v3, v151
	v_mov_b32_e32 v4, v151
	v_mov_b32_e32 v5, v151
	v_mov_b32_e32 v6, v151
	v_mov_b32_e32 v7, v151
	v_mov_b32_e32 v8, v151
	v_mov_b32_e32 v15, v151
	v_mov_b64_e32 v[32:33], v[16:17]
	v_mov_b64_e32 v[48:49], v[16:17]
	v_mov_b64_e32 v[64:65], v[16:17]
	v_mov_b64_e32 v[30:31], v[14:15]
	v_mov_b64_e32 v[28:29], v[12:13]
	v_mov_b64_e32 v[26:27], v[10:11]
	v_mov_b64_e32 v[24:25], v[8:9]
	v_mov_b64_e32 v[22:23], v[6:7]
	v_mov_b64_e32 v[20:21], v[4:5]
	v_mov_b64_e32 v[18:19], v[2:3]
	v_mov_b64_e32 v[46:47], v[14:15]
	v_mov_b64_e32 v[44:45], v[12:13]
	v_mov_b64_e32 v[42:43], v[10:11]
	v_mov_b64_e32 v[40:41], v[8:9]
	v_mov_b64_e32 v[38:39], v[6:7]
	v_mov_b64_e32 v[36:37], v[4:5]
	v_mov_b64_e32 v[34:35], v[2:3]
	v_mov_b64_e32 v[62:63], v[14:15]
	v_mov_b64_e32 v[60:61], v[12:13]
	v_mov_b64_e32 v[58:59], v[10:11]
	v_mov_b64_e32 v[56:57], v[8:9]
	v_mov_b64_e32 v[54:55], v[6:7]
	v_mov_b64_e32 v[52:53], v[4:5]
	v_mov_b64_e32 v[50:51], v[2:3]
	s_mov_b32 s99, 0
.LBB0_937:
	s_and_b32 s4, s2, 1
	s_mul_i32 s0, s4, 0x6400
	s_add_i32 s5, s0, 0
	s_mul_i32 s6, s4, 0xffffec00
	s_add_i32 s6, s5, s6
	s_add_i32 s1, s3, s2
	s_xor_b32 s100, s4, 1
	s_mul_i32 s101, s100, 0x5000
	s_mul_i32 s100, s100, 0x6400
	s_cmp_eq_u32 s99, 0
	s_mov_b32 s99, 0
	s_cbranch_scc0 .Lst_win_top
	v_add3_u32 v66, s5, v187, v165
	s_waitcnt vmcnt(3)
	ds_write_b128 v66, v[130:133]
	v_add3_u32 v66, s5, v207, v165
	s_waitcnt vmcnt(2)
	ds_write_b128 v66, v[134:137]
	v_add3_u32 v66, s6, v208, v165
	s_waitcnt vmcnt(1)
	ds_write_b128 v66, v[138:141] offset:51200
	v_add3_u32 v66, s6, v209, v165
	s_waitcnt vmcnt(0)
	ds_write_b128 v66, v[142:145] offset:51200
.Lst_win_top:
	s_cmp_ge_u32 s1, s68
	s_cselect_b32 s98, 0, 1
	s_waitcnt lgkmcnt(0)
	s_barrier
	s_cbranch_scc1 .LBB0_939
	s_add_i32 s1, s1, 1
	s_mul_hi_u32 s5, s1, 0x60000
	s_mul_i32 s1, s1, 0x60000
	s_add_u32 s6, s90, s1
	s_addc_u32 s7, s91, s5
	s_add_u32 s8, s92, s1
	v_lshl_add_u64 v[66:67], s[6:7], 0, v[146:147]
	s_addc_u32 s9, s93, s5
	v_lshl_add_u64 v[66:67], v[66:67], 0, v[150:151]
	v_lshl_add_u64 v[68:69], s[6:7], 0, v[162:163]
	v_lshl_add_u64 v[68:69], v[68:69], 0, v[150:151]
	global_load_dwordx4 v[130:133], v[66:67], off
	global_load_dwordx4 v[134:137], v[68:69], off
	v_lshl_add_u64 v[66:67], s[8:9], 0, v[146:147]
	v_lshl_add_u64 v[66:67], v[66:67], 0, v[150:151]
	v_lshl_add_u64 v[68:69], s[8:9], 0, v[162:163]
	v_lshl_add_u64 v[68:69], v[68:69], 0, v[150:151]
	global_load_dwordx4 v[138:141], v[66:67], off
	global_load_dwordx4 v[142:145], v[68:69], off

; #define LAS __attribute__((address_space(3)))
; template <bool HASP, bool HASV>
; __device__ __forceinline__ void stage_store(const Stage& st, LAS unsigned char* kbuf, LAS unsigned char* vbuf, int tid) {
;     const int r0 = tid >> 4, c0 = (tid & 15) * 16;
;     *(LAS u32x4*)(kbuf + r0 * KP + c0) = st.k0; *(LAS u32x4*)(kbuf + (r0 + 32) * KP + c0) = st.k1;
;     if (HASP) *(LAS u32x4*)(kbuf + (tid >> 3) * KP + 256 + (tid & 7) * 16) = st.kp;
;     if (HASV) { *(LAS u32x4*)(vbuf + r0 * VP + c0) = st.v0; *(LAS u32x4*)(vbuf + (r0 + 32) * VP + c0) = st.v1; }
; }
.LBB0_943:
	s_cmp_eq_u32 s98, 0
	s_cbranch_scc1 .Lst_win_mid
	v_add3_u32 v254, s100, v187, v165
	s_waitcnt vmcnt(3)
	ds_write_b128 v254, v[130:133]
	v_add3_u32 v254, s100, v207, v165
	s_waitcnt vmcnt(2)
	ds_write_b128 v254, v[134:137]
	v_add3_u32 v254, s101, v208, v165
	s_waitcnt vmcnt(1)
	ds_write_b128 v254, v[138:141] offset:51200
	v_add3_u32 v254, s101, v209, v165
	s_waitcnt vmcnt(0)
	ds_write_b128 v254, v[142:145] offset:51200
	s_mov_b32 s99, 1

; #define LAS __attribute__((address_space(3)))
; template <int MODE, int NQ> ...
;     ...
;     int j; unsigned long long rem = 0ull;
;     if (MODE == M_SEL) { rem = tmask; j = rem ? (int)__builtin_ctzll(rem) : -1; rem &= rem - 1ull; } else { j = jlo <= jhi ? jlo : -1; }
;     Stage st;
;     __syncthreads();
;     if (j >= 0) stage_load<HASP, HASV>(st, Kg + (size_t)j * 64 * ldk, ldk, Pg + (size_t)j * 64 * 64, Vg + (size_t)j * 64 * ldv, ldv, tid);
;     int it = 0;
;     while (j >= 0) {
;         const int bsel = it & 1;
;         stage_store<HASP, HASV>(st, lds + OFF_K + bsel * KBUF, lds + OFF_V + bsel * VBUF, tid);
;         __syncthreads();
;         int jn;
;         if (MODE == M_SEL) { jn = rem ? (int)__builtin_ctzll(rem) : -1; rem &= rem - 1ull; } else { jn = (j + 1 <= jhi) ? j + 1 : -1; }
;         if (jn >= 0) stage_load<HASP, HASV>(st, Kg + (size_t)jn * 64 * ldk, ldk, Pg + (size_t)jn * 64 * 64, Vg + (size_t)jn * 64 * ldv, ldv, tid);
; __device__ __forceinline__ void mla_unit(Frame& F, int b, int hd, int qb) {
;     unsigned char* ws = F.ws; LAS unsigned char* lds = F.lds;
;     int tid = F.tid; asm volatile("" : "+v"(tid));
;     const int lane = tid & 63, w = __builtin_amdgcn_readfirstlane(tid >> 6), ql = lane & 31, hi = lane >> 5;
;     const int ts = 256 * qb + 32 * w + ql; const size_t trow = (size_t)b * S + ts;
;     const float C = 0.07216878364870322f * LOG2E;
;     bf16x8 qf[12];
;     { const bf16_t* qrow = (const bf16_t*)(ws + WS_QMLA) + trow * 3072 + hd * 192 + 8 * hi;
; #pragma unroll
;       for (int d = 0; d < 12; ++d) qf[d] = *(const bf16x8*)(qrow + 16 * d); }
;     const bf16_t* KN = (const bf16_t*)(ws + WS_KN) + (size_t)b * S * 2048 + hd * 128; const bf16_t* VM = (const bf16_t*)(ws + WS_VM) + (size_t)b * S * 2048 + hd * 128;
;     const bf16_t* KPE = (const bf16_t*)(ws + WS_KPE) + (size_t)b * S * 64;
;     f32x16 O[4]; float m = -1e30f, l = 0.f; zero_o(O);
;     run_seq<M_MLA, 12>(lds, tid, qf, O, m, l, C, KN, 2048, KPE, VM, 2048, 0, 4 * qb + 3, 0ull, ts, -1, 0ull, 256 * qb + 32 * w + 31, 0.f, 0, 0);
.LBB0_961:
	s_xor_b64 s[92:93], s[0:1], -1
	s_and_b64 s[0:1], s[0:1], exec
	v_mov_b32_e32 v16, v0
	s_cselect_b32 s2, s94, s81
	v_readfirstlane_b32 s0, v16
	s_ashr_i32 s0, s0, 1
	s_lshl_b32 s97, s2, 8
	s_andn2_b32 s0, s0, 31
	v_and_b32_e32 v4, 31, v16
	s_add_i32 s3, s0, s97
	v_or_b32_e32 v170, s3, v4
	v_ashrrev_i32_e32 v171, 31, v170
	v_lshl_add_u64 v[172:173], s[72:73], 0, v[170:171]
	v_bfe_u32 v17, v16, 5, 1
	v_mad_u64_u32 v[2:3], s[0:1], v172, s75, v[168:169]
	v_mad_i32_i24 v3, v173, s75, v3
	v_lshlrev_b32_e32 v166, 4, v17
	v_lshl_add_u64 v[2:3], v[2:3], 0, v[166:167]
	global_load_dwordx4 v[98:101], v[2:3], off
	global_load_dwordx4 v[102:105], v[2:3], off offset:32
	global_load_dwordx4 v[106:109], v[2:3], off offset:64
	global_load_dwordx4 v[110:113], v[2:3], off offset:96
	global_load_dwordx4 v[114:117], v[2:3], off offset:128
	global_load_dwordx4 v[118:121], v[2:3], off offset:160
	global_load_dwordx4 v[122:125], v[2:3], off offset:192
	global_load_dwordx4 v[126:129], v[2:3], off offset:224
	global_load_dwordx4 v[130:133], v[2:3], off offset:256
	global_load_dwordx4 v[134:137], v[2:3], off offset:288
	global_load_dwordx4 v[138:141], v[2:3], off offset:320
	global_load_dwordx4 v[142:145], v[2:3], off offset:352
	v_mul_u32_u24_e32 v2, 0x190, v4
	v_add3_u32 v171, 0, v2, v166
	v_ashrrev_i32_e32 v2, 4, v16
	v_ashrrev_i32_e32 v3, 31, v2
	v_lshlrev_b64 v[4:5], 12, v[2:3]
	v_lshlrev_b32_e32 v3, 4, v16
	s_mov_b64 s[0:1], 0x20000
	v_lshl_add_u64 v[6:7], s[84:85], 0, v[4:5]
	v_and_b32_e32 v166, 0xf0, v3
	v_lshl_add_u64 v[8:9], v[4:5], 0, s[0:1]
	v_lshl_add_u64 v[6:7], v[6:7], 0, v[166:167]
	v_lshl_add_u64 v[10:11], s[84:85], 0, v[8:9]
	s_barrier
	v_lshl_add_u64 v[10:11], v[10:11], 0, v[166:167]
	global_load_dwordx4 v[146:149], v[6:7], off
	global_load_dwordx4 v[150:153], v[10:11], off
	v_ashrrev_i32_e32 v6, 3, v16
	v_ashrrev_i32_e32 v7, 31, v6
	v_lshlrev_b64 v[10:11], 7, v[6:7]
	v_lshl_add_u64 v[12:13], s[88:89], 0, v[10:11]
	v_and_b32_e32 v176, 0x70, v3
	v_mov_b32_e32 v177, v167
	v_lshl_add_u64 v[8:9], s[86:87], 0, v[8:9]
	v_lshl_add_u64 v[12:13], v[12:13], 0, v[176:177]
	v_lshl_add_u64 v[14:15], s[86:87], 0, v[4:5]
	v_lshl_add_u64 v[8:9], v[8:9], 0, v[166:167]
	v_lshl_add_u64 v[14:15], v[14:15], 0, v[166:167]
	global_load_dwordx4 v[154:157], v[12:13], off
	global_load_dwordx4 v[158:161], v[14:15], off
	global_load_dwordx4 v[162:165], v[8:9], off
	v_lshlrev_b32_e32 v174, 2, v17
	v_lshrrev_b32_e32 v3, 2, v16
	v_and_b32_e32 v7, 16, v16
	v_lshlrev_b32_e32 v8, 2, v16
	s_lshl_b32 s0, s2, 2
	v_and_or_b32 v3, v3, 3, v174
	v_and_or_b32 v7, v8, 12, v7
	s_or_b32 s95, s0, 3
	v_mul_u32_u24_e32 v3, 0x140, v3
	v_lshlrev_b32_e32 v7, 1, v7
	v_mul_lo_u32 v183, v6, s76
	s_movk_i32 s0, 0x140
	v_and_b32_e32 v6, 7, v16
	v_add3_u32 v175, 0, v3, v7
	v_mul_lo_u32 v177, v2, s76
	v_mul_lo_u32 v184, v2, s0
	v_lshl_add_u64 v[2:3], s[90:91], 0, v[10:11]
	v_lshlrev_b32_e32 v6, 4, v6
	v_mov_b32_e32 v7, v167
	v_lshl_add_u64 v[178:179], v[2:3], 0, v[6:7]
	v_lshl_add_u64 v[2:3], s[82:83], 0, v[4:5]
	v_and_b32_e32 v4, 15, v16
	v_lshlrev_b32_e32 v4, 4, v4
	v_mov_b32_e32 v5, v167
	v_mov_b32_e32 v16, v167
	v_mov_b32_e32 v17, v167
	v_lshl_add_u64 v[180:181], v[2:3], 0, v[4:5]
	v_mov_b32_e32 v2, v167
	v_mov_b32_e32 v3, v167
	v_mov_b32_e32 v4, v167
	v_mov_b32_e32 v6, v167
	v_mov_b32_e32 v8, v167
	v_mov_b32_e32 v9, v167
	v_mov_b32_e32 v10, v167
	v_mov_b32_e32 v11, v167
	v_mov_b32_e32 v12, v167
	v_mov_b32_e32 v13, v167
	v_mov_b32_e32 v14, v167
	v_mov_b32_e32 v15, v167
	v_mov_b64_e32 v[32:33], v[16:17]
	v_mov_b64_e32 v[48:49], v[16:17]
	v_mov_b64_e32 v[64:65], v[16:17]
	s_or_b32 s96, s3, 31
	v_add_u32_e32 v182, 0x3200, v177
	v_add_u32_e32 v185, 0x2800, v184
	s_addk_i32 s97, 0x100
	v_sub_u32_e32 v187, v170, v174
	s_mov_b32 s33, 0
	v_mov_b32_e32 v188, 0
	v_mov_b32_e32 v190, 0xf149f2ca
	v_mov_b64_e32 v[30:31], v[14:15]
	v_mov_b64_e32 v[28:29], v[12:13]
	v_mov_b64_e32 v[26:27], v[10:11]
	v_mov_b64_e32 v[24:25], v[8:9]
	v_mov_b64_e32 v[22:23], v[6:7]
	v_mov_b64_e32 v[20:21], v[4:5]
	v_mov_b64_e32 v[18:19], v[2:3]
	v_mov_b64_e32 v[46:47], v[14:15]
	v_mov_b64_e32 v[44:45], v[12:13]
	v_mov_b64_e32 v[42:43], v[10:11]
	v_mov_b64_e32 v[40:41], v[8:9]
	v_mov_b64_e32 v[38:39], v[6:7]
	v_mov_b64_e32 v[36:37], v[4:5]
	v_mov_b64_e32 v[34:35], v[2:3]
	v_mov_b64_e32 v[62:63], v[14:15]
	v_mov_b64_e32 v[60:61], v[12:13]
	v_mov_b64_e32 v[58:59], v[10:11]
	v_mov_b64_e32 v[56:57], v[8:9]
	v_mov_b64_e32 v[54:55], v[6:7]
	v_mov_b64_e32 v[52:53], v[4:5]
	v_mov_b64_e32 v[50:51], v[2:3]
	s_mov_b32 s64, 0
	s_mov_b32 s99, 0
.LBB0_962:
	s_and_b32 s65, s64, 1
	s_mul_i32 s0, s65, 0x6400
	s_add_i32 s1, s0, 0
	s_mul_i32 s2, s65, 0xffffec00
	s_add_i32 s2, s1, s2
	s_xor_b32 s100, s65, 1
	s_mul_i32 s101, s100, 0x5000
	s_mul_i32 s100, s100, 0x6400
	s_cmp_eq_u32 s99, 0
	s_mov_b32 s99, 0
	s_cbranch_scc0 .Lst_mla_top
	v_add3_u32 v66, s1, v177, v166
	s_waitcnt vmcnt(4)
	ds_write_b128 v66, v[146:149]
	v_add3_u32 v66, s1, v182, v166
	s_waitcnt vmcnt(3)
	ds_write_b128 v66, v[150:153]
	v_add3_u32 v66, s1, v183, v176
	s_waitcnt vmcnt(2)
	ds_write_b128 v66, v[154:157] offset:256
	v_add3_u32 v66, s2, v184, v166
	s_waitcnt vmcnt(1)
	ds_write_b128 v66, v[158:161] offset:51200
	v_add3_u32 v66, s2, v185, v166
	s_waitcnt vmcnt(0)
	ds_write_b128 v66, v[162:165] offset:51200
.Lst_mla_top:
	s_cmp_ge_u32 s64, s95
	s_cselect_b32 s98, 0, 1
	s_waitcnt lgkmcnt(0)
	s_barrier
	s_cbranch_scc1 .LBB0_964
	v_lshl_add_u64 v[66:67], s[30:31], 0, v[180:181]
	v_add_co_u32_e32 v68, vcc, 0x34840000, v66
	s_nop 1
	v_addc_co_u32_e32 v69, vcc, 0, v67, vcc
	v_add_co_u32_e32 v70, vcc, 0x34860000, v66
	s_nop 1
	v_addc_co_u32_e32 v71, vcc, 0, v67, vcc
	global_load_dwordx4 v[146:149], v[68:69], off
	global_load_dwordx4 v[150:153], v[70:71], off
	v_add_co_u32_e32 v70, vcc, 0x38840000, v66
	v_lshl_add_u64 v[68:69], s[30:31], 0, v[178:179]
	s_nop 0
	v_addc_co_u32_e32 v71, vcc, 0, v67, vcc
	v_add_co_u32_e32 v66, vcc, 0x38860000, v66
	global_load_dwordx4 v[154:157], v[68:69], off
	global_load_dwordx4 v[158:161], v[70:71], off
	v_addc_co_u32_e32 v67, vcc, 0, v67, vcc
	global_load_dwordx4 v[162:165], v[66:67], off

; #define LAS __attribute__((address_space(3)))
; template <bool HASP, bool HASV>
; __device__ __forceinline__ void stage_store(const Stage& st, LAS unsigned char* kbuf, LAS unsigned char* vbuf, int tid) {
;     const int r0 = tid >> 4, c0 = (tid & 15) * 16;
;     *(LAS u32x4*)(kbuf + r0 * KP + c0) = st.k0; *(LAS u32x4*)(kbuf + (r0 + 32) * KP + c0) = st.k1;
;     if (HASP) *(LAS u32x4*)(kbuf + (tid >> 3) * KP + 256 + (tid & 7) * 16) = st.kp;
;     if (HASV) { *(LAS u32x4*)(vbuf + r0 * VP + c0) = st.v0; *(LAS u32x4*)(vbuf + (r0 + 32) * VP + c0) = st.v1; }
; }
.LBB0_969:
	s_cmp_eq_u32 s98, 0
	s_cbranch_scc1 .Lst_mla_mid
	v_add3_u32 v254, s100, v177, v166
	s_waitcnt vmcnt(4)
	ds_write_b128 v254, v[146:149]
	v_add3_u32 v254, s100, v182, v166
	s_waitcnt vmcnt(3)
	ds_write_b128 v254, v[150:153]
	v_add3_u32 v254, s100, v183, v176
	s_waitcnt vmcnt(2)
	ds_write_b128 v254, v[154:157] offset:256
	v_add3_u32 v254, s101, v184, v166
	s_waitcnt vmcnt(1)
	ds_write_b128 v254, v[158:161] offset:51200
	v_add3_u32 v254, s101, v185, v166
	s_waitcnt vmcnt(0)
	ds_write_b128 v254, v[162:165] offset:51200
	s_mov_b32 s99, 1
